# k33: k28 + barrier audit: GEMM-phase exit s_barrier kept only on the no-grid-barrier path (both grid-barrier paths start with their own waitcnt+s_barrier)
# speedup vs baseline: 1.0025x; 1.0025x over previous
.LBB0_424:
	v_readlane_b32 s0, v252, 15
	v_readlane_b32 s1, v252, 16
	s_and_b64 s[0:1], s[0:1], s[68:69]
	s_add_i32 s2, s96, 1
	s_cmp_lt_i32 s2, s97
	s_cselect_b64 s[2:3], -1, 0
	s_and_b64 s[0:1], s[0:1], s[2:3]
	s_andn2_b64 vcc, exec, s[0:1]
	s_cbranch_vccz .Lk33_cont
	s_barrier
	s_branch .LBB0_9
.Lk33_cont:
	v_readlane_b32 s0, v252, 62
	v_readlane_b32 s1, v252, 63
	s_andn2_b64 vcc, exec, s[0:1]
	s_cbranch_vccnz .LBB0_437
	s_waitcnt vmcnt(0) lgkmcnt(0)
	s_barrier
	s_mov_b64 s[0:1], exec
	v_readlane_b32 s2, v254, 58
	v_readlane_b32 s3, v254, 59
	s_and_b64 s[2:3], s[0:1], s[2:3]
	s_mov_b64 exec, s[2:3]
	s_cbranch_execz .LBB0_436
	v_readlane_b32 s2, v252, 1
	v_readlane_b32 s3, v252, 2
	buffer_wbl2 sc1
	s_load_dwordx2 s[2:3], s[2:3], 0x58
	s_mov_b64 s[4:5], exec
	v_mbcnt_lo_u32_b32 v1, s4, 0
	v_mbcnt_hi_u32_b32 v1, s5, v1
	v_cmp_eq_u32_e32 vcc, 0, v1
	s_waitcnt lgkmcnt(0)
	global_load_dword v0, v145, s[2:3] offset:40
	s_and_saveexec_b64 s[6:7], vcc
	s_cbranch_execz .LBB0_429
	s_bcnt1_i32_b64 s4, s[4:5]
	v_mov_b32_e32 v2, s4
	global_atomic_add v2, v145, v2, s[2:3] offset:32 sc0
